# tight barrier polling: s_sleep removed from the eleven fast-path group-barrier poll loops
# baseline (speedup 1.0000x reference)
; __device__ __forceinline__ unsigned xb_ld(unsigned* p)              { return __hip_atomic_load(p, __ATOMIC_RELAXED, __HIP_MEMORY_SCOPE_AGENT); }
; #define XB_SPIN(cond, bar) do { unsigned _sp = 0; while (cond) { __builtin_amdgcn_s_sleep(1); \
;     if ((++_sp & 255u) == 0u) { if (xb_ld(&(bar)[XB_TMO])) break; if (_sp > XB_SPIN_CAP) { atomicAdd(&(bar)[XB_TMO], 1u); break; } } } } while (0)
; __device__ __forceinline__ void grp_barrier(const XcdBarrier& b, unsigned gsz) {
;     ...
;             XB_SPIN(xb_ld(&bar[XB_XGEN(b.x)]) == gen, bar);
.Lgb_poll0:
	s_waitcnt vmcnt(0)
	v_sub_u32_e32 v3, v7, v6
	v_cmp_gt_i32_e32 vcc, 0, v3
	s_cbranch_vccz .Lgb_done0
	s_nop 0
	s_add_u32 s3, s3, 1
	s_cmp_lt_u32 s3, 0x40000
	s_cbranch_scc0 .Lgb_done0
	global_load_dword v7, v202, s[8:9] offset:1024 sc1
	s_branch .Lgb_poll0

; __device__ __forceinline__ unsigned xb_ld(unsigned* p)              { return __hip_atomic_load(p, __ATOMIC_RELAXED, __HIP_MEMORY_SCOPE_AGENT); }
; #define XB_SPIN(cond, bar) do { unsigned _sp = 0; while (cond) { __builtin_amdgcn_s_sleep(1); \
;     if ((++_sp & 255u) == 0u) { if (xb_ld(&(bar)[XB_TMO])) break; if (_sp > XB_SPIN_CAP) { atomicAdd(&(bar)[XB_TMO], 1u); break; } } } } while (0)
; __device__ __forceinline__ void grp_barrier(const XcdBarrier& b, unsigned gsz) {
;     ...
;             XB_SPIN(xb_ld(&bar[XB_XGEN(b.x)]) == gen, bar);
.Lgb_poll7:
	s_waitcnt vmcnt(0)
	v_sub_u32_e32 v3, v7, v6
	v_cmp_gt_i32_e32 vcc, 0, v3
	s_cbranch_vccz .Lgb_done7
	s_nop 0
	s_add_u32 s3, s3, 1
	s_cmp_lt_u32 s3, 0x40000
	s_cbranch_scc0 .Lgb_done7
	global_load_dword v7, v202, s[12:13] offset:1024 sc1
	s_branch .Lgb_poll7

; __device__ __forceinline__ unsigned xb_ld(unsigned* p)              { return __hip_atomic_load(p, __ATOMIC_RELAXED, __HIP_MEMORY_SCOPE_AGENT); }
; #define XB_SPIN(cond, bar) do { unsigned _sp = 0; while (cond) { __builtin_amdgcn_s_sleep(1); \
;     if ((++_sp & 255u) == 0u) { if (xb_ld(&(bar)[XB_TMO])) break; if (_sp > XB_SPIN_CAP) { atomicAdd(&(bar)[XB_TMO], 1u); break; } } } } while (0)
; __device__ __forceinline__ void grp_barrier(const XcdBarrier& b, unsigned gsz) {
;     ...
;             XB_SPIN(xb_ld(&bar[XB_XGEN(b.x)]) == gen, bar);
.Lgb_poll9:
	s_waitcnt vmcnt(0)
	v_sub_u32_e32 v3, v7, v6
	v_cmp_gt_i32_e32 vcc, 0, v3
	s_cbranch_vccz .Lgb_done9
	s_nop 0
	s_add_u32 s3, s3, 1
	s_cmp_lt_u32 s3, 0x40000
	s_cbranch_scc0 .Lgb_done9
	global_load_dword v7, v202, s[10:11] offset:1024 sc1
	s_branch .Lgb_poll9
